# first-barrier XCD discovery: the 16 arrival-counter loads issued back to back with one wait instead of a wait after each
# speedup vs baseline: 1.0028x; 1.0028x over previous
; __device__ __forceinline__ unsigned xb_ld(unsigned* p)              { return __hip_atomic_load(p, __ATOMIC_RELAXED, __HIP_MEMORY_SCOPE_AGENT); }
; __device__ __forceinline__ void xcd_barrier_complete(unsigned* bar, unsigned x, unsigned& nloc, unsigned& nx) {
;     const unsigned G = gridDim.x * gridDim.y * gridDim.z;
;     unsigned sum, cnt, mine, sp = 0u;
;     for (;;) {
;         sum = 0u; cnt = 0u; mine = 0u;
; #pragma unroll
;         for (unsigned j = 0; j < 16; ++j) { const unsigned c = xb_ld(&bar[XB_XCNT(j)]); sum += c; cnt += (c > 0u) ? 1u : 0u; mine = (j == x) ? c : mine; }
;         if (sum == G) break;
;         __builtin_amdgcn_s_sleep(1);
;         if ((++sp & 255u) == 0u) { if (xb_ld(&bar[XB_TMO])) break; if (sp > XB_SPIN_CAP) { atomicAdd(&bar[XB_TMO], 1u); break; } }
;     }
;     nloc = mine > 0u ? mine : 1u; nx = cnt > 0u ? cnt : 1u;
; }
.LBB0_556:
	s_mov_b64 s[6:7], -1
	v_readlane_b32 s4, v251, 15
	v_readlane_b32 s5, v251, 16
	s_nop 4
	global_load_dword v0, v3, s[4:5] sc1
	v_readlane_b32 s4, v251, 17
	v_readlane_b32 s5, v251, 18
	s_nop 4
	global_load_dword v1, v3, s[4:5] sc1
	v_readlane_b32 s4, v251, 19
	v_readlane_b32 s5, v251, 20
	s_nop 4
	global_load_dword v2, v3, s[4:5] sc1
	v_readlane_b32 s4, v251, 21
	v_readlane_b32 s5, v251, 22
	s_nop 4
	global_load_dword v4, v3, s[4:5] sc1
	v_readlane_b32 s4, v251, 23
	v_readlane_b32 s5, v251, 24
	s_nop 4
	global_load_dword v5, v3, s[4:5] sc1
	v_readlane_b32 s4, v251, 25
	v_readlane_b32 s5, v251, 26
	s_nop 4
	global_load_dword v6, v3, s[4:5] sc1
	v_readlane_b32 s4, v251, 27
	v_readlane_b32 s5, v251, 28
	s_nop 4
	global_load_dword v7, v3, s[4:5] sc1
	v_readlane_b32 s4, v251, 29
	v_readlane_b32 s5, v251, 30
	s_nop 4
	global_load_dword v8, v3, s[4:5] sc1
	v_readlane_b32 s4, v251, 31
	v_readlane_b32 s5, v251, 32
	s_nop 4
	global_load_dword v9, v3, s[4:5] sc1
	v_readlane_b32 s4, v251, 33
	v_readlane_b32 s5, v251, 34
	s_nop 4
	global_load_dword v10, v3, s[4:5] sc1
	v_readlane_b32 s4, v251, 35
	v_readlane_b32 s5, v251, 36
	s_nop 4
	global_load_dword v11, v3, s[4:5] sc1
	v_readlane_b32 s4, v251, 37
	v_readlane_b32 s5, v251, 38
	s_nop 4
	global_load_dword v12, v3, s[4:5] sc1
	v_readlane_b32 s4, v251, 39
	v_readlane_b32 s5, v251, 40
	s_nop 4
	global_load_dword v13, v3, s[4:5] sc1
	v_readlane_b32 s4, v251, 41
	v_readlane_b32 s5, v251, 42
	s_nop 4
	global_load_dword v14, v3, s[4:5] sc1
	v_readlane_b32 s4, v251, 43
	v_readlane_b32 s5, v251, 44
	s_nop 4
	global_load_dword v15, v3, s[4:5] sc1
	v_readlane_b32 s4, v251, 45
	v_readlane_b32 s5, v251, 46
	s_nop 4
	global_load_dword v16, v3, s[4:5] sc1
	s_mov_b64 s[4:5], -1
	s_waitcnt vmcnt(0)
	v_add_u32_e32 v17, v1, v0
	v_add_u32_e32 v17, v17, v2
	v_add_u32_e32 v17, v17, v4
	v_add_u32_e32 v17, v17, v5
	v_add_u32_e32 v17, v17, v6
	v_add_u32_e32 v17, v17, v7
	v_add_u32_e32 v17, v17, v8
	v_add_u32_e32 v17, v17, v9
	v_add_u32_e32 v17, v17, v10
	v_add_u32_e32 v17, v17, v11
	v_add_u32_e32 v17, v17, v12
	v_add_u32_e32 v17, v17, v13
	v_add_u32_e32 v17, v17, v14
	v_add_u32_e32 v17, v17, v15
	v_add_u32_e32 v17, v17, v16
	v_cmp_eq_u32_e32 vcc, s10, v17
	s_cbranch_vccnz .LBB0_555
	s_and_b32 s4, s28, 0xff
	s_cmp_eq_u32 s4, 0
	s_mov_b64 s[4:5], -1
	s_mov_b64 s[8:9], -1
	s_sleep 1
	s_cbranch_scc0 .LBB0_560
	v_readlane_b32 s4, v251, 13
	v_readlane_b32 s5, v251, 14
	s_nop 4
	global_load_dword v17, v3, s[4:5] sc1
	s_waitcnt vmcnt(0)
	v_cmp_eq_u32_e32 vcc, 0, v17
	s_cbranch_vccnz .LBB0_562
	s_mov_b64 s[8:9], 0
	s_mov_b64 s[4:5], -1
